# gemm_in plain tiles: bf16 image read back into registers, row stores issued during the next tile's K-loop (2 per iteration); tile-loop tails no longer reload gridDim / drain stores
# baseline (speedup 1.0000x reference)
.LBB0_33:
	s_or_b64 exec, exec, s[2:3]
	s_add_u32 s0, s78, 0x1a00
	s_addc_u32 s1, s79, 0
	v_writelane_b32 v236, s0, 1
	v_sub_u32_e32 v2, 0, v166
	s_mov_b32 s41, 0
	v_writelane_b32 v236, s1, 2
	v_readlane_b32 s0, v237, 57
	v_readlane_b32 s4, v237, 61
	v_readlane_b32 s5, v237, 62
	s_add_u32 s0, s4, 0x3840
	v_readlane_b32 s1, v237, 58
	v_readlane_b32 s7, v236, 0
	v_writelane_b32 v236, s0, 3
	s_addc_u32 s0, s5, 0
	v_writelane_b32 v236, s0, 4
	v_lshl_add_u64 v[0:1], v[0:1], 2, s[4:5]
	s_mov_b64 s[0:1], 0x1400
	v_lshl_add_u64 v[168:169], v[0:1], 0, s[0:1]
	s_mov_b64 s[0:1], 0x2400
	v_lshl_add_u64 v[170:171], v[0:1], 0, s[0:1]
	s_add_u32 s0, s4, 0x200
	s_addc_u32 s1, s5, 0
	v_writelane_b32 v236, s0, 5
	v_cvt_f32_u32_e32 v0, v166
	v_cvt_f32_u32_e32 v1, v162
	v_writelane_b32 v236, s1, 6
	s_add_u32 s0, s4, 0x3400
	s_addc_u32 s1, s5, 0
	v_writelane_b32 v236, s0, 7
	v_rcp_iflag_f32_e32 v0, v0
	v_rcp_iflag_f32_e32 v1, v1
	v_writelane_b32 v236, s1, 8
	s_add_u32 s0, s4, 0x3500
	s_addc_u32 s1, s5, 0
	v_writelane_b32 v236, s0, 9
	v_mul_f32_e32 v0, 0x4f7ffffe, v0
	v_cvt_u32_f32_e32 v0, v0
	v_writelane_b32 v236, s1, 10
	s_mov_b64 s[0:1], 0
	v_writelane_b32 v236, s0, 11
	v_mul_f32_e32 v1, 0x4f7ffffe, v1
	v_cvt_u32_f32_e32 v3, v1
	v_writelane_b32 v236, s1, 12
	v_writelane_b32 v236, s44, 13
	v_mul_lo_u32 v2, v2, v0
	v_mul_hi_u32 v2, v0, v2
	v_writelane_b32 v236, s45, 14
	v_writelane_b32 v236, s46, 15
	v_writelane_b32 v236, s47, 16
	v_writelane_b32 v236, s48, 17
	v_writelane_b32 v236, s49, 18
	v_writelane_b32 v236, s50, 19
	v_writelane_b32 v236, s51, 20
	v_writelane_b32 v236, s52, 21
	v_writelane_b32 v236, s53, 22
	v_writelane_b32 v236, s54, 23
	v_writelane_b32 v236, s55, 24
	v_writelane_b32 v236, s56, 25
	v_writelane_b32 v236, s57, 26
	v_writelane_b32 v236, s58, 27
	v_writelane_b32 v236, s59, 28
	v_writelane_b32 v236, s76, 29
	v_add_u32_e32 v172, v0, v2
	v_sub_u32_e32 v0, 0, v162
	v_writelane_b32 v236, s77, 30
	v_writelane_b32 v236, s78, 31
	v_writelane_b32 v236, s79, 32
	v_writelane_b32 v236, s80, 33
	v_writelane_b32 v236, s81, 34
	v_writelane_b32 v236, s82, 35
	v_writelane_b32 v236, s83, 36
	v_writelane_b32 v236, s84, 37
	v_writelane_b32 v236, s85, 38
	v_writelane_b32 v236, s86, 39
	v_writelane_b32 v236, s87, 40
	v_mul_lo_u32 v0, v0, v3
	v_writelane_b32 v236, s88, 41
	v_mul_hi_u32 v0, v3, v0
	v_writelane_b32 v236, s89, 42
	v_add_u32_e32 v174, v3, v0
	v_writelane_b32 v236, s90, 43
	v_readlane_b32 s6, v237, 63
	v_mbcnt_lo_u32_b32 v0, -1, 0
	v_writelane_b32 v236, s91, 44
	v_mov_b32_e32 v1, 0
	s_movk_i32 s33, 0x70
	s_movk_i32 s36, 0x3ff
	s_mov_b32 s37, 0x5a000
	s_movk_i32 s38, 0x1680
	s_mov_b32 s39, 0x2d000
	s_mov_b32 s42, 0x87000
	s_movk_i32 s43, 0x880
	v_mov_b32_e32 v167, 0x358637bd
	s_movk_i32 s92, 0x480
	s_movk_i32 s93, 0x3300
	v_mov_b32_e32 v173, 0x3c0881c4
	v_mov_b32_e32 v175, 0xbab64f3b
	s_movk_i32 s94, 0x2080
	s_movk_i32 s95, 0x3000
	v_mov_b32_e32 v192, 1
	v_mbcnt_hi_u32_b32 v193, -1, v0
	v_mov_b32_e32 v194, 0x7f800000
	v_not_b32_e32 v195, 63
	v_not_b32_e32 v196, 31
	v_mov_b32_e32 v197, 0x7fc00000
	v_mov_b32_e32 v198, 0x3300
	v_mov_b32_e32 v176, 0xfe00
	v_mov_b32_e32 v199, 0xf149f2ca
	v_mov_b32_e32 v200, 0x6080
	v_mov_b32_e32 v201, 0xff800000
	v_mov_b32_e32 v202, 0x461c4000
	v_mov_b32_e32 v203, 0xb00
	v_mov_b32_e32 v204, 0x200
	v_mov_b32_e32 v205, 0x100
	v_mov_b64_e32 v[178:179], 0x3460
	v_mov_b64_e32 v[180:181], 0x3400
	s_mov_b32 s6, s41
	v_writelane_b32 v234, s41, 22
	v_writelane_b32 v234, s41, 23
	v_readfirstlane_b32 s0, v164
	v_readfirstlane_b32 s1, v165
	s_nop 4
	s_load_dword s0, s[0:1], 0x0
	s_waitcnt lgkmcnt(0)
	v_writelane_b32 v234, s0, 21
	v_writelane_b32 v236, s34, 45
	v_readlane_b32 s2, v237, 59
	v_readlane_b32 s3, v237, 60
	v_writelane_b32 v236, s35, 46
	s_branch .LBB0_35

.LBB0_48:
	v_mov_b32_e32 v0, v163
	s_waitcnt vmcnt(7)
	v_mov_b32_e32 v35, v163
	v_lshlrev_b32_e32 v36, 7, v136
	v_ashrrev_i32_e32 v34, 1, v35
	v_and_b32_e32 v34, 0xffffffc0, v34
	v_lshl_add_u32 v34, v135, 7, v34
	v_and_or_b32 v34, v0, 15, v34
	v_lshrrev_b32_e32 v0, 2, v0
	v_and_b32_e32 v35, 64, v35
	v_and_b32_e32 v0, 12, v0
	v_or3_b32 v36, v35, v36, v0
	v_ashrrev_i32_e32 v35, 31, v34
	s_waitcnt vmcnt(6)
	v_lshlrev_b64 v[38:39], 12, v[34:35]
	v_ashrrev_i32_e32 v37, 31, v36
	v_lshl_add_u64 v[38:39], s[44:45], 0, v[38:39]
	v_lshlrev_b64 v[36:37], 2, v[36:37]
	s_waitcnt vmcnt(5)
	v_lshl_add_u64 v[46:47], v[38:39], 0, v[36:37]
	global_load_dwordx4 v[38:41], v[46:47], off
	s_waitcnt vmcnt(0)
	v_pk_add_f32 v[38:39], v[94:95], v[38:39]
	v_pk_add_f32 v[40:41], v[96:97], v[40:41]
	global_store_dwordx4 v[46:47], v[38:41], off
	global_load_dwordx4 v[38:41], v[46:47], off offset:64
	s_waitcnt vmcnt(0)
	v_pk_add_f32 v[38:39], v[90:91], v[38:39]
	v_pk_add_f32 v[40:41], v[92:93], v[40:41]
	global_store_dwordx4 v[46:47], v[38:41], off offset:64
	global_load_dwordx4 v[38:41], v[46:47], off offset:128
	s_waitcnt vmcnt(0)
	v_pk_add_f32 v[38:39], v[86:87], v[38:39]
	v_pk_add_f32 v[40:41], v[88:89], v[40:41]
	global_store_dwordx4 v[46:47], v[38:41], off offset:128
	global_load_dwordx4 v[38:41], v[46:47], off offset:192
	s_waitcnt vmcnt(0)
	v_pk_add_f32 v[38:39], v[82:83], v[38:39]
	v_pk_add_f32 v[40:41], v[84:85], v[40:41]
	global_store_dwordx4 v[46:47], v[38:41], off offset:192
	s_nop 1
	v_or_b32_e32 v38, 16, v34
	v_ashrrev_i32_e32 v39, 31, v38
	v_lshlrev_b64 v[38:39], 12, v[38:39]
	v_lshl_add_u64 v[38:39], s[44:45], 0, v[38:39]
	v_lshl_add_u64 v[46:47], v[38:39], 0, v[36:37]
	global_load_dwordx4 v[38:41], v[46:47], off
	s_waitcnt vmcnt(0)
	v_pk_add_f32 v[38:39], v[74:75], v[38:39]
	v_pk_add_f32 v[40:41], v[76:77], v[40:41]
	global_store_dwordx4 v[46:47], v[38:41], off
	global_load_dwordx4 v[38:41], v[46:47], off offset:64
	s_waitcnt vmcnt(0)
	v_pk_add_f32 v[38:39], v[70:71], v[38:39]
	v_pk_add_f32 v[40:41], v[72:73], v[40:41]
	global_store_dwordx4 v[46:47], v[38:41], off offset:64
	global_load_dwordx4 v[38:41], v[46:47], off offset:128
	s_waitcnt vmcnt(0)
	v_pk_add_f32 v[38:39], v[58:59], v[38:39]
	v_pk_add_f32 v[40:41], v[60:61], v[40:41]
	global_store_dwordx4 v[46:47], v[38:41], off offset:128
	global_load_dwordx4 v[38:41], v[46:47], off offset:192
	s_waitcnt vmcnt(0)
	v_pk_add_f32 v[38:39], v[42:43], v[38:39]
	v_pk_add_f32 v[40:41], v[44:45], v[40:41]
	global_store_dwordx4 v[46:47], v[38:41], off offset:192
	s_nop 1
	v_or_b32_e32 v38, 32, v34
	v_ashrrev_i32_e32 v39, 31, v38
	v_lshlrev_b64 v[38:39], 12, v[38:39]
	v_lshl_add_u64 v[38:39], s[44:45], 0, v[38:39]
	v_lshl_add_u64 v[42:43], v[38:39], 0, v[36:37]
	global_load_dwordx4 v[38:41], v[42:43], off
	s_waitcnt vmcnt(0)
	v_pk_add_f32 v[30:31], v[30:31], v[38:39]
	v_pk_add_f32 v[32:33], v[32:33], v[40:41]
	global_store_dwordx4 v[42:43], v[30:33], off
	global_load_dwordx4 v[30:33], v[42:43], off offset:64
	s_waitcnt vmcnt(0)
	v_pk_add_f32 v[26:27], v[26:27], v[30:31]
	v_pk_add_f32 v[28:29], v[28:29], v[32:33]
	global_store_dwordx4 v[42:43], v[26:29], off offset:64
	global_load_dwordx4 v[26:29], v[42:43], off offset:128
	s_waitcnt vmcnt(0)
	v_pk_add_f32 v[22:23], v[22:23], v[26:27]
	v_pk_add_f32 v[24:25], v[24:25], v[28:29]
	global_store_dwordx4 v[42:43], v[22:25], off offset:128
	global_load_dwordx4 v[22:25], v[42:43], off offset:192
	s_waitcnt vmcnt(0)
	v_pk_add_f32 v[18:19], v[18:19], v[22:23]
	v_pk_add_f32 v[20:21], v[20:21], v[24:25]
	global_store_dwordx4 v[42:43], v[18:21], off offset:192
	s_nop 1
	v_or_b32_e32 v18, 48, v34
	v_ashrrev_i32_e32 v19, 31, v18
	v_lshlrev_b64 v[18:19], 12, v[18:19]
	v_lshl_add_u64 v[18:19], s[44:45], 0, v[18:19]
	v_lshl_add_u64 v[22:23], v[18:19], 0, v[36:37]
	global_load_dwordx4 v[18:21], v[22:23], off
	s_waitcnt vmcnt(0)
	v_pk_add_f32 v[14:15], v[14:15], v[18:19]
	v_pk_add_f32 v[16:17], v[16:17], v[20:21]
	global_store_dwordx4 v[22:23], v[14:17], off
	global_load_dwordx4 v[14:17], v[22:23], off offset:64
	s_waitcnt vmcnt(0)
	v_pk_add_f32 v[10:11], v[10:11], v[14:15]
	v_pk_add_f32 v[12:13], v[12:13], v[16:17]
	global_store_dwordx4 v[22:23], v[10:13], off offset:64
	global_load_dwordx4 v[10:13], v[22:23], off offset:128
	s_waitcnt vmcnt(0)
	v_pk_add_f32 v[6:7], v[6:7], v[10:11]
	v_pk_add_f32 v[8:9], v[8:9], v[12:13]
	global_store_dwordx4 v[22:23], v[6:9], off offset:128
	global_load_dwordx4 v[6:9], v[22:23], off offset:192
	s_waitcnt vmcnt(0)
	v_pk_add_f32 v[2:3], v[2:3], v[6:7]
	v_pk_add_f32 v[4:5], v[4:5], v[8:9]
	global_store_dwordx4 v[22:23], v[2:5], off offset:192
	v_readlane_b32 vcc_lo, v234, 21
	s_nop 0
	v_mov_b32_e32 v0, vcc_lo
	v_add_u32_e32 v134, vcc_lo, v134
	v_cmp_lt_i32_e32 vcc, s36, v134
	s_or_b64 s[0:1], vcc, s[0:1]
	s_andn2_b64 exec, exec, s[0:1]
	s_cbranch_execz .LBB0_52

.LBB0_58:
	s_waitcnt vmcnt(6)
	v_mul_f32_e32 v62, 0xbfb8aa3b, v92
	v_exp_f32_e32 v62, v62
	v_mov_b32_e32 v0, v163
	v_mov_b32_e32 v59, v163
	v_add_f32_e32 v62, 1.0, v62
	v_and_b32_e32 v60, 15, v0
	v_lshrrev_b32_e32 v59, 1, v59
	v_lshrrev_b32_e32 v0, 2, v0
	v_rcp_f32_e32 v62, v62
	v_lshlrev_b32_e32 v58, 6, v136
	v_and_b32_e32 v61, 32, v59
	v_and_b32_e32 v0, 12, v0
	v_or3_b32 v0, v0, v61, v58
	s_mov_b32 s2, 0xfffffc0
	v_and_or_b32 v59, v59, s2, v60
	v_lshlrev_b32_e32 v0, 1, v0
	v_lshlrev_b32_e32 v60, 7, v136
	v_sub_u32_e32 v0, v0, v60
	v_mul_f32_e32 v60, 0xbfb8aa3b, v90
	v_mul_f32_e32 v61, 0xbfb8aa3b, v91
	v_mul_f32_e32 v62, v92, v62
	v_exp_f32_e32 v60, v60
	v_exp_f32_e32 v61, v61
	v_mul_f32_e32 v63, v88, v62
	v_mul_f32_e32 v62, 0xbfb8aa3b, v93
	v_exp_f32_e32 v62, v62
	v_add_f32_e32 v60, 1.0, v60
	v_add_f32_e32 v61, 1.0, v61
	v_rcp_f32_e32 v60, v60
	v_rcp_f32_e32 v61, v61
	v_add_f32_e32 v62, 1.0, v62
	v_rcp_f32_e32 v62, v62
	v_mul_f32_e32 v60, v90, v60
	v_mul_f32_e32 v61, v91, v61
	v_mul_f32_e32 v60, v86, v60
	v_mul_f32_e32 v61, v87, v61
	v_mul_f32_e32 v62, v93, v62
	s_movk_i32 s4, 0x90
	v_mul_f32_e32 v64, v89, v62
	v_cvt_pk_bf16_f32 v62, v60, v61
	v_mad_u64_u32 v[60:61], s[2:3], v59, s4, v[0:1]
	v_mul_f32_e32 v0, 0xbfb8aa3b, v54
	v_exp_f32_e32 v0, v0
	v_cvt_pk_bf16_f32 v63, v63, v64
	v_ashrrev_i32_e32 v59, 31, v58
	v_add_f32_e32 v0, 1.0, v0
	v_rcp_f32_e32 v0, v0
	s_nop 0
	v_mul_f32_e32 v0, v54, v0
	v_mul_f32_e32 v0, v50, v0
	v_mul_f32_e32 v50, 0xbfb8aa3b, v55
	v_exp_f32_e32 v50, v50
	s_nop 0
	v_add_f32_e32 v50, 1.0, v50
	v_rcp_f32_e32 v50, v50
	s_nop 0
	v_mul_f32_e32 v50, v55, v50
	v_mul_f32_e32 v50, v51, v50
	v_cvt_pk_bf16_f32 v50, v0, v50
	v_mul_f32_e32 v0, 0xbfb8aa3b, v46
	v_exp_f32_e32 v0, v0
	v_mul_f32_e32 v51, 0xbfb8aa3b, v56
	v_exp_f32_e32 v51, v51
	v_add_f32_e32 v0, 1.0, v0
	v_rcp_f32_e32 v0, v0
	v_add_f32_e32 v51, 1.0, v51
	v_rcp_f32_e32 v51, v51
	v_mul_f32_e32 v0, v46, v0
	v_mul_f32_e32 v0, v42, v0
	v_mul_f32_e32 v42, 0xbfb8aa3b, v47
	v_exp_f32_e32 v42, v42
	v_mul_f32_e32 v51, v56, v51
	v_mul_f32_e32 v51, v52, v51
	v_mul_f32_e32 v52, 0xbfb8aa3b, v57
	v_add_f32_e32 v42, 1.0, v42
	v_rcp_f32_e32 v42, v42
	v_exp_f32_e32 v52, v52
	v_mul_f32_e32 v42, v47, v42
	v_mul_f32_e32 v42, v43, v42
	v_cvt_pk_bf16_f32 v42, v0, v42
	v_mul_f32_e32 v0, 0xbfb8aa3b, v38
	v_exp_f32_e32 v0, v0
	v_mul_f32_e32 v43, 0xbfb8aa3b, v48
	v_exp_f32_e32 v43, v43
	v_add_f32_e32 v52, 1.0, v52
	v_add_f32_e32 v0, 1.0, v0
	v_rcp_f32_e32 v0, v0
	v_add_f32_e32 v43, 1.0, v43
	v_rcp_f32_e32 v43, v43
	v_rcp_f32_e32 v52, v52
	v_mul_f32_e32 v0, v38, v0
	v_mul_f32_e32 v0, v34, v0
	v_mul_f32_e32 v34, 0xbfb8aa3b, v39
	v_exp_f32_e32 v34, v34
	v_mul_f32_e32 v43, v48, v43
	v_mul_f32_e32 v43, v44, v43
	v_mul_f32_e32 v44, 0xbfb8aa3b, v49
	v_add_f32_e32 v34, 1.0, v34
	v_rcp_f32_e32 v34, v34
	v_exp_f32_e32 v44, v44
	v_mul_f32_e32 v52, v57, v52
	v_mul_f32_e32 v52, v53, v52
	v_mul_f32_e32 v34, v39, v34
	v_mul_f32_e32 v34, v35, v34
	v_mul_f32_e32 v35, 0xbfb8aa3b, v40
	v_exp_f32_e32 v35, v35
	v_add_f32_e32 v44, 1.0, v44
	v_rcp_f32_e32 v44, v44
	v_cvt_pk_bf16_f32 v34, v0, v34
	v_add_f32_e32 v35, 1.0, v35
	v_rcp_f32_e32 v35, v35
	v_mul_f32_e32 v44, v49, v44
	v_add_u32_e32 v0, 0x800, v60
	v_mul_f32_e32 v44, v45, v44
	v_mul_f32_e32 v35, v40, v35
	v_mul_f32_e32 v35, v36, v35
	v_mul_f32_e32 v36, 0xbfb8aa3b, v41
	v_exp_f32_e32 v36, v36
	v_cvt_pk_bf16_f32 v43, v43, v44
	v_cvt_pk_bf16_f32 v51, v51, v52
	ds_write2_b64 v60, v[62:63], v[50:51] offset1:4
	v_add_f32_e32 v36, 1.0, v36
	v_rcp_f32_e32 v36, v36
	s_nop 0
	v_mul_f32_e32 v36, v41, v36
	v_mul_f32_e32 v36, v37, v36
	v_cvt_pk_bf16_f32 v35, v35, v36
	ds_write2_b64 v0, v[42:43], v[34:35] offset0:32 offset1:36
	v_mul_f32_e32 v0, 0xbfb8aa3b, v30
	v_exp_f32_e32 v0, v0
	s_nop 0
	v_add_f32_e32 v0, 1.0, v0
	v_rcp_f32_e32 v0, v0
	s_nop 0
	v_mul_f32_e32 v0, v30, v0
	v_mul_f32_e32 v0, v26, v0
	v_mul_f32_e32 v26, 0xbfb8aa3b, v31
	v_exp_f32_e32 v26, v26
	s_nop 0
	v_add_f32_e32 v26, 1.0, v26
	v_rcp_f32_e32 v26, v26
	s_nop 0
	v_mul_f32_e32 v26, v31, v26
	v_mul_f32_e32 v26, v27, v26
	v_cvt_pk_bf16_f32 v26, v0, v26
	v_mul_f32_e32 v0, 0xbfb8aa3b, v22
	v_exp_f32_e32 v0, v0
	v_mul_f32_e32 v27, 0xbfb8aa3b, v32
	v_exp_f32_e32 v27, v27
	v_add_f32_e32 v0, 1.0, v0
	v_rcp_f32_e32 v0, v0
	v_add_f32_e32 v27, 1.0, v27
	v_rcp_f32_e32 v27, v27
	v_mul_f32_e32 v0, v22, v0
	v_mul_f32_e32 v0, v18, v0
	v_mul_f32_e32 v18, 0xbfb8aa3b, v23
	v_exp_f32_e32 v18, v18
	v_mul_f32_e32 v27, v32, v27
	v_mul_f32_e32 v27, v28, v27
	v_mul_f32_e32 v28, 0xbfb8aa3b, v33
	v_add_f32_e32 v18, 1.0, v18
	v_rcp_f32_e32 v18, v18
	v_exp_f32_e32 v28, v28
	v_mul_f32_e32 v18, v23, v18
	v_mul_f32_e32 v18, v19, v18
	v_mul_f32_e32 v19, 0xbfb8aa3b, v24
	v_exp_f32_e32 v19, v19
	v_add_f32_e32 v28, 1.0, v28
	v_rcp_f32_e32 v28, v28
	v_cvt_pk_bf16_f32 v18, v0, v18
	v_add_f32_e32 v19, 1.0, v19
	v_rcp_f32_e32 v19, v19
	v_mul_f32_e32 v28, v33, v28
	v_add_u32_e32 v0, 0x1000, v60
	v_mul_f32_e32 v28, v29, v28
	v_mul_f32_e32 v19, v24, v19
	v_mul_f32_e32 v19, v20, v19
	v_mul_f32_e32 v20, 0xbfb8aa3b, v25
	v_exp_f32_e32 v20, v20
	v_cvt_pk_bf16_f32 v27, v27, v28
	s_nop 0
	v_add_f32_e32 v20, 1.0, v20
	v_rcp_f32_e32 v20, v20
	s_nop 0
	v_mul_f32_e32 v20, v25, v20
	v_mul_f32_e32 v20, v21, v20
	v_cvt_pk_bf16_f32 v19, v19, v20
	ds_write2_b64 v0, v[26:27], v[18:19] offset0:64 offset1:68
	v_mul_f32_e32 v0, 0xbfb8aa3b, v10
	v_exp_f32_e32 v0, v0
	s_nop 0
	v_add_f32_e32 v0, 1.0, v0
	v_rcp_f32_e32 v0, v0
	s_nop 0
	v_mul_f32_e32 v0, v10, v0
	v_mul_f32_e32 v10, 0xbfb8aa3b, v11
	v_exp_f32_e32 v10, v10
	v_mul_f32_e32 v0, v14, v0
	v_add_f32_e32 v10, 1.0, v10
	v_rcp_f32_e32 v10, v10
	s_nop 0
	v_mul_f32_e32 v10, v11, v10
	v_mul_f32_e32 v10, v15, v10
	v_cvt_pk_bf16_f32 v10, v0, v10
	v_mul_f32_e32 v0, 0xbfb8aa3b, v2
	v_exp_f32_e32 v0, v0
	v_mul_f32_e32 v11, 0xbfb8aa3b, v12
	v_exp_f32_e32 v11, v11
	v_add_f32_e32 v0, 1.0, v0
	v_rcp_f32_e32 v0, v0
	v_add_f32_e32 v11, 1.0, v11
	v_rcp_f32_e32 v11, v11
	v_mul_f32_e32 v0, v2, v0
	v_mul_f32_e32 v2, 0xbfb8aa3b, v3
	v_exp_f32_e32 v2, v2
	v_mul_f32_e32 v11, v12, v11
	v_mul_f32_e32 v12, 0xbfb8aa3b, v13
	v_exp_f32_e32 v12, v12
	v_add_f32_e32 v2, 1.0, v2
	v_rcp_f32_e32 v2, v2
	v_mul_f32_e32 v11, v16, v11
	v_add_f32_e32 v12, 1.0, v12
	v_rcp_f32_e32 v12, v12
	v_mul_f32_e32 v2, v3, v2
	v_mul_f32_e32 v3, 0xbfb8aa3b, v4
	v_exp_f32_e32 v3, v3
	v_mul_f32_e32 v12, v13, v12
	v_mul_f32_e32 v0, v6, v0
	v_mul_f32_e32 v2, v7, v2
	v_add_f32_e32 v3, 1.0, v3
	v_rcp_f32_e32 v3, v3
	v_mul_f32_e32 v12, v17, v12
	v_cvt_pk_bf16_f32 v11, v11, v12
	v_cvt_pk_bf16_f32 v2, v0, v2
	v_mul_f32_e32 v3, v4, v3
	v_mul_f32_e32 v4, 0xbfb8aa3b, v5
	v_exp_f32_e32 v4, v4
	v_mul_f32_e32 v3, v8, v3
	v_add_u32_e32 v0, 0x1800, v60
	v_add_f32_e32 v4, 1.0, v4
	v_rcp_f32_e32 v4, v4
	s_nop 0
	v_mul_f32_e32 v4, v5, v4
	v_mul_f32_e32 v4, v9, v4
	v_cvt_pk_bf16_f32 v3, v3, v4
	ds_write2_b64 v0, v[10:11], v[2:3] offset0:96 offset1:100
	v_mov_b32_e32 v11, v163
	s_waitcnt lgkmcnt(0)
	s_barrier
	v_lshl_add_u64 v[2:3], v[58:59], 1, s[78:79]
	v_lshlrev_b32_e32 v0, 4, v11
	v_and_b32_e32 v0, 0x70, v0
	v_ashrrev_i32_e32 v8, 3, v11
	v_lshl_add_u64 v[6:7], v[2:3], 0, v[0:1]
	v_mad_u64_u32 v[2:3], s[2:3], v8, s4, v[0:1]
	ds_read_b128 v[2:5], v2
	v_lshlrev_b32_e32 v10, 7, v135
	v_add_u32_e32 v8, v8, v10
	v_mad_i64_i32 v[8:9], s[2:3], v8, s38, v[6:7]
	s_waitcnt lgkmcnt(0)
	global_store_dwordx4 v[8:9], v[2:5], off nt
	s_nop 1
	v_add_u32_e32 v2, 0x100, v11
	v_ashrrev_i32_e32 v8, 3, v2
	v_mad_u64_u32 v[2:3], s[2:3], v8, s4, v[0:1]
	ds_read_b128 v[2:5], v2
	v_add_u32_e32 v8, v8, v10
	v_mad_i64_i32 v[8:9], s[2:3], v8, s38, v[6:7]
	s_waitcnt lgkmcnt(0)
	global_store_dwordx4 v[8:9], v[2:5], off nt
	s_nop 1
	v_add_u32_e32 v2, 0x200, v11
	v_ashrrev_i32_e32 v8, 3, v2
	v_mad_u64_u32 v[2:3], s[2:3], v8, s4, v[0:1]
	ds_read_b128 v[2:5], v2
	v_add_u32_e32 v8, v8, v10
	v_mad_i64_i32 v[8:9], s[2:3], v8, s38, v[6:7]
	s_waitcnt lgkmcnt(0)
	global_store_dwordx4 v[8:9], v[2:5], off nt
	s_nop 1
	v_add_u32_e32 v2, 0x300, v11
	v_ashrrev_i32_e32 v8, 3, v2
	v_mad_u64_u32 v[2:3], s[2:3], v8, s4, v[0:1]
	ds_read_b128 v[2:5], v2
	v_add_u32_e32 v0, v8, v10
	v_mad_i64_i32 v[6:7], s[2:3], v0, s38, v[6:7]
	s_movk_i32 s2, 0x15ff
	s_waitcnt lgkmcnt(0)
	global_store_dwordx4 v[6:7], v[2:5], off nt
	s_barrier
	v_readlane_b32 vcc_lo, v234, 21
	s_nop 0
	v_mov_b32_e32 v0, vcc_lo
	v_add_u32_e32 v134, vcc_lo, v134
	v_cmp_lt_i32_e32 vcc, s2, v134
	s_or_b64 s[0:1], vcc, s[0:1]
	s_andn2_b64 exec, exec, s[0:1]
	s_cbranch_execz .LBB0_67

.LBB0_91:
	v_mov_b32_e32 v16, v163
	ds_write2_b64 v137, v[126:127], v[122:123] offset1:4
	ds_write2_b64 v137, v[118:119], v[114:115] offset0:8 offset1:12
	ds_write2_b64 v138, v[110:111], v[106:107] offset0:32 offset1:36
	ds_write2_b64 v138, v[102:103], v[98:99] offset0:40 offset1:44
	ds_write2_b64 v139, v[100:101], v[104:105] offset0:64 offset1:68
	ds_write2_b64 v139, v[108:109], v[112:113] offset0:72 offset1:76
	ds_write2_b64 v140, v[116:117], v[120:121] offset0:96 offset1:100
	ds_write2_b64 v140, v[124:125], v[128:129] offset0:104 offset1:108
	s_waitcnt lgkmcnt(0)
	s_barrier
	s_movk_i32 s4, 0x110
	v_lshlrev_b32_e32 v0, 4, v16
	v_and_b32_e32 v0, 0xf0, v0
	v_ashrrev_i32_e32 v4, 4, v16
	v_mad_u64_u32 v[2:3], s[2:3], v4, s4, v[0:1]
	v_add_u32_e32 v3, v4, v136
	v_mov_b64_e32 v[10:11], s[80:81]
	v_mad_i64_i32 v[4:5], s[2:3], v3, s43, v[10:11]
	v_lshlrev_b64 v[12:13], 1, v[184:185]
	v_lshl_add_u64 v[4:5], v[4:5], 0, v[12:13]
	v_lshl_add_u64 v[14:15], v[4:5], 0, v[0:1]
	ds_read_b128 v[2:5], v2
	v_add_u32_e32 v6, 0x100, v16
	v_ashrrev_i32_e32 v17, 4, v6
	v_mad_u64_u32 v[6:7], s[2:3], v17, s4, v[0:1]
	ds_read_b128 v[6:9], v6
	s_waitcnt lgkmcnt(1)
	global_store_dwordx4 v[14:15], v[2:5], off
	s_nop 1
	v_add_u32_e32 v2, v17, v136
	v_mad_i64_i32 v[2:3], s[2:3], v2, s43, v[10:11]
	v_lshl_add_u64 v[2:3], v[2:3], 0, v[12:13]
	v_lshl_add_u64 v[2:3], v[2:3], 0, v[0:1]
	s_waitcnt lgkmcnt(0)
	global_store_dwordx4 v[2:3], v[6:9], off
	v_add_u32_e32 v2, 0x200, v16
	v_ashrrev_i32_e32 v4, 4, v2
	v_mad_u64_u32 v[2:3], s[2:3], v4, s4, v[0:1]
	v_add_u32_e32 v3, v4, v136
	v_mad_i64_i32 v[4:5], s[2:3], v3, s43, v[10:11]
	v_lshl_add_u64 v[4:5], v[4:5], 0, v[12:13]
	v_lshl_add_u64 v[14:15], v[4:5], 0, v[0:1]
	ds_read_b128 v[2:5], v2
	v_add_u32_e32 v6, 0x300, v16
	v_ashrrev_i32_e32 v17, 4, v6
	v_mad_u64_u32 v[6:7], s[2:3], v17, s4, v[0:1]
	ds_read_b128 v[6:9], v6
	s_waitcnt lgkmcnt(1)
	global_store_dwordx4 v[14:15], v[2:5], off
	s_nop 1
	v_add_u32_e32 v2, v17, v136
	v_mad_i64_i32 v[2:3], s[2:3], v2, s43, v[10:11]
	v_lshl_add_u64 v[2:3], v[2:3], 0, v[12:13]
	v_lshl_add_u64 v[2:3], v[2:3], 0, v[0:1]
	s_waitcnt lgkmcnt(0)
	global_store_dwordx4 v[2:3], v[6:9], off
	v_add_u32_e32 v2, 0x400, v16
	v_ashrrev_i32_e32 v4, 4, v2
	v_mad_u64_u32 v[2:3], s[2:3], v4, s4, v[0:1]
	v_add_u32_e32 v3, v4, v136
	v_mad_i64_i32 v[4:5], s[2:3], v3, s43, v[10:11]
	v_lshl_add_u64 v[4:5], v[4:5], 0, v[12:13]
	v_lshl_add_u64 v[14:15], v[4:5], 0, v[0:1]
	ds_read_b128 v[2:5], v2
	v_add_u32_e32 v6, 0x500, v16
	v_ashrrev_i32_e32 v17, 4, v6
	v_mad_u64_u32 v[6:7], s[2:3], v17, s4, v[0:1]
	ds_read_b128 v[6:9], v6
	s_waitcnt lgkmcnt(1)
	global_store_dwordx4 v[14:15], v[2:5], off
	s_nop 1
	v_add_u32_e32 v2, v17, v136
	v_mad_i64_i32 v[2:3], s[2:3], v2, s43, v[10:11]
	v_lshl_add_u64 v[2:3], v[2:3], 0, v[12:13]
	v_lshl_add_u64 v[2:3], v[2:3], 0, v[0:1]
	s_waitcnt lgkmcnt(0)
	global_store_dwordx4 v[2:3], v[6:9], off
	v_add_u32_e32 v2, 0x600, v16
	v_ashrrev_i32_e32 v4, 4, v2
	v_mad_u64_u32 v[2:3], s[2:3], v4, s4, v[0:1]
	v_add_u32_e32 v3, v4, v136
	v_mad_i64_i32 v[4:5], s[2:3], v3, s43, v[10:11]
	v_lshl_add_u64 v[4:5], v[4:5], 0, v[12:13]
	v_lshl_add_u64 v[14:15], v[4:5], 0, v[0:1]
	ds_read_b128 v[2:5], v2
	v_add_u32_e32 v6, 0x700, v16
	v_ashrrev_i32_e32 v16, 4, v6
	v_mad_u64_u32 v[6:7], s[2:3], v16, s4, v[0:1]
	ds_read_b128 v[6:9], v6
	s_waitcnt lgkmcnt(1)
	global_store_dwordx4 v[14:15], v[2:5], off
	s_nop 1
	v_add_u32_e32 v2, v16, v136
	v_mad_i64_i32 v[2:3], s[2:3], v2, s43, v[10:11]
	v_lshl_add_u64 v[2:3], v[2:3], 0, v[12:13]
	v_lshl_add_u64 v[2:3], v[2:3], 0, v[0:1]
	s_waitcnt lgkmcnt(0)
	global_store_dwordx4 v[2:3], v[6:9], off
	s_barrier
	v_readlane_b32 vcc_lo, v234, 21
	s_nop 0
	v_mov_b32_e32 v0, vcc_lo
	v_add_u32_e32 v177, vcc_lo, v177
	v_cmp_lt_i32_e32 vcc, s36, v177
	s_or_b64 s[0:1], vcc, s[0:1]
	s_andn2_b64 exec, exec, s[0:1]
	s_cbranch_execz .LBB0_119

.LBB0_392:
	s_or_b64 exec, exec, s[6:7]
	v_readlane_b32 vcc_lo, v234, 21
	s_movk_i32 s0, 0x19ff
	v_mov_b32_e32 v0, vcc_lo
	v_add_u32_e32 v134, vcc_lo, v134
	v_cmp_lt_i32_e32 vcc, s0, v134
	s_or_b64 s[2:3], vcc, s[2:3]
	s_andn2_b64 exec, exec, s[2:3]
	s_cbranch_execz .LBB0_453

.LBB0_398:
	v_mov_b64_e32 v[2:3], s[80:81]
	s_mov_b32 s4, 0x44000
	v_mad_u64_u32 v[4:5], s[0:1], v136, s4, v[2:3]
	v_mov_b64_e32 v[2:3], s[46:47]
	v_mad_i64_i32 v[6:7], s[0:1], v135, s4, v[2:3]
	v_mov_b32_e32 v2, v163
	s_mov_b32 s4, 0x22000
	v_ashrrev_i32_e32 v3, 3, v2
	v_lshlrev_b32_e32 v0, 4, v2
	v_mad_i64_i32 v[4:5], s[0:1], v3, s43, v[4:5]
	v_and_b32_e32 v0, 0x70, v0
	v_lshl_add_u64 v[130:131], v[4:5], 0, v[0:1]
	v_mad_i64_i32 v[4:5], s[0:1], v3, s43, v[6:7]
	v_lshl_add_u64 v[132:133], v[4:5], 0, v[0:1]
	v_and_b32_e32 v110, 7, v163
	v_bfe_u32 v111, v163, 4, 3
	v_xor_b32_e32 v111, v111, v110
	v_sub_u32_e32 v111, v111, v110
	v_lshlrev_b32_e32 v111, 4, v111
	v_lshrrev_b32_e32 v112, 6, v163
	v_lshlrev_b32_e32 v112, 10, v112
	v_readfirstlane_b32 s0, v130
	v_readfirstlane_b32 s1, v131
	v_readfirstlane_b32 s4, v132
	v_readfirstlane_b32 s5, v133
	v_readfirstlane_b32 s8, v112
	s_nop 3
	v_subrev_u32_e32 v98, s0, v130
	v_subrev_u32_e32 v102, s4, v132
	v_add_u32_e32 v98, v98, v111
	v_add_u32_e32 v102, v102, v111
	v_add_u32_e32 v99, 0x11000, v98
	v_add_u32_e32 v103, 0x11000, v102
	v_add_u32_e32 v100, 0x22000, v98
	v_add_u32_e32 v104, 0x22000, v102
	v_add_u32_e32 v101, 0x33000, v98
	v_add_u32_e32 v105, 0x33000, v102
	v_lshlrev_b32_e32 v110, 3, v163
	v_lshlrev_b32_e32 v111, 7, v163
	v_and_b32_e32 v112, 0x2000, v111
	v_and_b32_e32 v111, 0x780, v111
	v_and_b32_e32 v107, 64, v110
	v_xor_b32_e32 v110, v110, v163
	v_and_b32_e32 v110, 48, v110
	v_or3_b32 v110, v111, v107, v110
	v_lshlrev_b32_e32 v111, 6, v163
	v_and_b32_e32 v111, 0xffffe000, v111
	v_or_b32_e32 v108, v110, v112
	v_or_b32_e32 v106, v110, v111
	v_xor_b32_e32 v107, 64, v106
	v_xor_b32_e32 v109, 64, v108
	s_mov_b32 m0, s8
	s_nop 0
	global_load_lds_dwordx4 v98, s[0:1]
	s_add_u32 m0, s8, 0x1000
	s_nop 0
	global_load_lds_dwordx4 v99, s[0:1]
	s_add_u32 m0, s8, 0x2000
	s_nop 0
	global_load_lds_dwordx4 v100, s[0:1]
	s_add_u32 m0, s8, 0x3000
	s_nop 0
	global_load_lds_dwordx4 v101, s[0:1]
	s_add_u32 m0, s8, 0x4000
	s_nop 0
	global_load_lds_dwordx4 v102, s[4:5]
	s_add_u32 m0, s8, 0x5000
	s_nop 0
	global_load_lds_dwordx4 v103, s[4:5]
	s_add_u32 m0, s8, 0x6000
	s_nop 0
	global_load_lds_dwordx4 v104, s[4:5]
	s_add_u32 m0, s8, 0x7000
	s_nop 0
	global_load_lds_dwordx4 v105, s[4:5]
	s_waitcnt vmcnt(0)
	s_add_u32 s0, s0, 0x80
	s_addc_u32 s1, s1, 0
	s_add_u32 s4, s4, 0x80
	s_addc_u32 s5, s5, 0
	s_barrier
	s_add_u32 m0, s8, 0x8000
	ds_read_b128 v[142:145], v106
	ds_read_b128 v[158:161], v108 offset:16384
	s_nop 0
	global_load_lds_dwordx4 v98, s[0:1]
	s_add_u32 m0, s8, 0x9000
	ds_read_b128 v[182:185], v108 offset:18432
	ds_read_b128 v[186:189], v108 offset:20480
	s_nop 0
	global_load_lds_dwordx4 v99, s[0:1]
	s_add_u32 m0, s8, 0xa000
	ds_read_b128 v[206:209], v108 offset:22528
	ds_read_b128 v[146:149], v106 offset:2048
	s_nop 0
	global_load_lds_dwordx4 v100, s[0:1]
	s_add_u32 m0, s8, 0xb000
	ds_read_b128 v[150:153], v106 offset:4096
	ds_read_b128 v[154:157], v106 offset:6144
	s_nop 0
	global_load_lds_dwordx4 v101, s[0:1]
	s_add_u32 m0, s8, 0xc000
	s_nop 0
	global_load_lds_dwordx4 v102, s[4:5]
	s_add_u32 m0, s8, 0xd000
	s_nop 0
	global_load_lds_dwordx4 v103, s[4:5]
	s_add_u32 m0, s8, 0xe000
	s_nop 0
	global_load_lds_dwordx4 v104, s[4:5]
	s_add_u32 m0, s8, 0xf000
	s_nop 0
	global_load_lds_dwordx4 v105, s[4:5]
	s_add_u32 s0, s0, 0x80
	s_addc_u32 s1, s1, 0
	s_add_u32 s4, s4, 0x80
	s_addc_u32 s5, s5, 0
	s_waitcnt lgkmcnt(0)
	v_mfma_f32_16x16x32_bf16 v[94:97], v[158:161], v[142:145], 0
	ds_read_b128 v[50:53], v107
	ds_read_b128 v[66:69], v109 offset:16384
	v_mfma_f32_16x16x32_bf16 v[90:93], v[182:185], v[142:145], 0
	v_mfma_f32_16x16x32_bf16 v[86:89], v[186:189], v[142:145], 0
	ds_read_b128 v[70:73], v109 offset:18432
	ds_read_b128 v[78:81], v109 offset:20480
	v_mfma_f32_16x16x32_bf16 v[74:77], v[206:209], v[142:145], 0
	v_mfma_f32_16x16x32_bf16 v[46:49], v[158:161], v[146:149], 0
	ds_read_b128 v[82:85], v109 offset:22528
	ds_read_b128 v[54:57], v107 offset:2048
	v_mfma_f32_16x16x32_bf16 v[42:45], v[182:185], v[146:149], 0
	v_mfma_f32_16x16x32_bf16 v[38:41], v[186:189], v[146:149], 0
	ds_read_b128 v[58:61], v107 offset:4096
	ds_read_b128 v[62:65], v107 offset:6144
	v_mfma_f32_16x16x32_bf16 v[34:37], v[206:209], v[146:149], 0
	v_mfma_f32_16x16x32_bf16 v[30:33], v[158:161], v[150:153], 0
	v_mfma_f32_16x16x32_bf16 v[26:29], v[182:185], v[150:153], 0
	v_mfma_f32_16x16x32_bf16 v[22:25], v[186:189], v[150:153], 0
	v_mfma_f32_16x16x32_bf16 v[18:21], v[206:209], v[150:153], 0
	v_mfma_f32_16x16x32_bf16 v[14:17], v[158:161], v[154:157], 0
	v_mfma_f32_16x16x32_bf16 v[10:13], v[182:185], v[154:157], 0
	v_mfma_f32_16x16x32_bf16 v[2:5], v[186:189], v[154:157], 0
	v_mfma_f32_16x16x32_bf16 v[6:9], v[206:209], v[154:157], 0
	s_waitcnt vmcnt(0) lgkmcnt(0)
	s_barrier
	s_movk_i32 s9, 7
	v_readlane_b32 s11, v234, 22
.Lg1_loop:
	s_cmp_eq_u32 s11, 0
	s_cbranch_scc1 .Lg1_dskip
	s_sub_u32 s10, 7, s9
	s_cmp_gt_u32 s10, 3
	s_cbranch_scc1 .Lg1_dskip
	s_cmp_eq_u32 s10, 0
	s_cbranch_scc1 .Lg1_d0
	s_cmp_eq_u32 s10, 1
	s_cbranch_scc1 .Lg1_d1
	s_cmp_eq_u32 s10, 2
	s_cbranch_scc1 .Lg1_d2
	global_store_dwordx4 v122, v[114:117], s[78:79] nt
	v_add_u32_e32 v122, 0x33000, v122
	global_store_dwordx4 v122, v[118:121], s[78:79] nt
	s_mov_b32 s11, 0
	v_writelane_b32 v234, s41, 22
	s_branch .Lg1_dskip
.Lg1_d0:
	global_store_dwordx4 v122, v[210:213], s[78:79] nt
	v_add_u32_e32 v122, 0x33000, v122
	global_store_dwordx4 v122, v[214:217], s[78:79] nt
	v_add_u32_e32 v122, 0x33000, v122
	s_branch .Lg1_dskip
.Lg1_d1:
	global_store_dwordx4 v122, v[218:221], s[78:79] nt
	v_add_u32_e32 v122, 0x33000, v122
	global_store_dwordx4 v122, v[222:225], s[78:79] nt
	v_add_u32_e32 v122, 0x33000, v122
	s_branch .Lg1_dskip
.Lg1_d2:
	global_store_dwordx4 v122, v[226:229], s[78:79] nt
	v_add_u32_e32 v122, 0x33000, v122
	global_store_dwordx4 v122, v[230:233], s[78:79] nt
	v_add_u32_e32 v122, 0x33000, v122

.LBB0_440:
	v_readfirstlane_b32 s12, v136
	v_readfirstlane_b32 s13, v135
	v_lshrrev_b32_e32 v5, 4, v163
	v_and_b32_e32 v6, 15, v163
	v_lshlrev_b32_e32 v6, 4, v6
	s_movk_i32 s14, 0x110
	v_mad_u32_u24 v7, v5, s14, v6
	ds_read_b128 v[210:213], v7
	ds_read_b128 v[214:217], v7 offset:4352
	ds_read_b128 v[218:221], v7 offset:8704
	ds_read_b128 v[222:225], v7 offset:13056
	ds_read_b128 v[226:229], v7 offset:17408
	ds_read_b128 v[230:233], v7 offset:21760
	ds_read_b128 v[114:117], v7 offset:26112
	ds_read_b128 v[118:121], v7 offset:30464
	s_lshl_b32 s12, s12, 7
	v_add_u32_e32 v5, s12, v5
	v_mul_u32_u24_e32 v122, 0x3300, v5
	s_lshl_b32 s13, s13, 8
	v_add3_u32 v122, v122, v6, s13
	s_mov_b32 s12, 1
	v_writelane_b32 v234, s12, 22
	s_andn2_b64 s[10:11], s[10:11], exec
	s_waitcnt lgkmcnt(0)

.LBB0_453:
	s_or_b64 exec, exec, s[2:3]
	v_readlane_b32 s0, v234, 22
	s_cmp_eq_u32 s0, 0
	s_cbranch_scc1 .Lg1_noflush
	global_store_dwordx4 v122, v[210:213], s[78:79] nt
	v_add_u32_e32 v122, 0x33000, v122
	global_store_dwordx4 v122, v[214:217], s[78:79] nt
	v_add_u32_e32 v122, 0x33000, v122
	global_store_dwordx4 v122, v[218:221], s[78:79] nt
	v_add_u32_e32 v122, 0x33000, v122
	global_store_dwordx4 v122, v[222:225], s[78:79] nt
	v_add_u32_e32 v122, 0x33000, v122
	global_store_dwordx4 v122, v[226:229], s[78:79] nt
	v_add_u32_e32 v122, 0x33000, v122
	global_store_dwordx4 v122, v[230:233], s[78:79] nt
	v_add_u32_e32 v122, 0x33000, v122
	global_store_dwordx4 v122, v[114:117], s[78:79] nt
	v_add_u32_e32 v122, 0x33000, v122
	global_store_dwordx4 v122, v[118:121], s[78:79] nt
	v_writelane_b32 v234, s41, 22
.Lg1_noflush:
.LBB0_454:
	s_mov_b64 s[0:1], 0
